# baseline (speedup 1.0000x reference)
; #define STAGE(Pp, BASE, br, kt) do { const u16* _g = (BASE) + ((long)(br) * K + (long)(kt) * BK); \
;     __builtin_amdgcn_global_load_lds((const unsigned*)(_g + voff0), (unsigned*)((char*)(Pp) + tb16), 16, 0, 0); \
;     __builtin_amdgcn_global_load_lds((const unsigned*)(_g + voff1), (unsigned*)((char*)(Pp) + tb16 + 8192), 16, 0, 0); } while (0)
; #define WAIT_V(n) asm volatile("s_waitcnt vmcnt(" #n ")" ::: "memory")
; #define BAR __builtin_amdgcn_s_barrier()
; template <int MODE> ...
;     ...
;     { int q = nwg / NXCD, r = nwg % NXCD, xcd = wgid % NXCD, off = wgid / NXCD;
;       wgid = (xcd < r ? xcd * (q + 1) : r * (q + 1) + (xcd - r) * q) + off; }
;     int nig = WGM * nN, gid = wgid / nig, fm = gid * WGM, gsz = min(nM - fm, WGM);
;     int pm = fm + ((wgid % nig) % gsz), pn = (wgid % nig) / gsz, brow = pm * BM, bcol = pn * BM;
;     f32x4 acc[2][2][4][2] = {};
;     bf16x8 At[4][2], B0[2][2], B1[2][2];
;     ...
;     STAGE(SB(0, 0), Bt, bcol, 0); STAGE(SA(0, 0), A, brow, 0); STAGE(SB(0, 1), Bt, bcol + HALF, 0); STAGE(SA(0, 1), A, brow + HALF, 0);
;     STAGE(SB(1, 0), Bt, bcol, 1); STAGE(SA(1, 0), A, brow, 1); STAGE(SB(1, 1), Bt, bcol + HALF, 1);
;     WAIT_V(6);
;     if (wr == 1) BAR;
;     BAR;
.LBB0_151:
	s_ashr_i32 s66, s82, 31
	s_lshr_b32 s66, s66, 29
	s_add_i32 s66, s82, s66
	s_ashr_i32 s67, s66, 3
	s_and_b32 s66, s66, -8
	s_sub_i32 s66, s82, s66
	s_cmp_lt_i32 s66, 0
	s_cselect_b32 s68, s35, 0xd0
	s_mul_i32 s66, s68, s66
	s_add_i32 s66, s66, s67
	s_mul_hi_i32 s67, s66, 0x4ec4ec4f
	s_lshr_b32 s68, s67, 31
	s_ashr_i32 s67, s67, 7
	s_add_i32 s67, s67, s68
	s_mul_i32 s68, s67, 0x1a0
	s_sub_i32 s83, s66, s68
	s_sext_i32_i16 s66, s83
	s_bfe_u32 s66, s66, 0x3001c
	s_add_i32 s66, s83, s66
	s_sext_i32_i16 s69, s66
	s_and_b32 s66, s66, 0xfff8
	s_sub_i32 s66, s83, s66
	s_sext_i32_i16 s66, s66
	s_lshl_b32 s67, s67, 11
	s_lshl_b32 s66, s66, 8
	s_add_i32 s68, s66, s67
	s_lshl_b32 s66, s69, 5
	s_and_b32 s66, s66, 0xffffff00
	s_ashr_i32 s67, s66, 31
	s_lshl_b64 s[74:75], s[66:67], 13
	s_add_u32 s70, s3, s74
	v_readfirstlane_b32 s69, v153
	s_addc_u32 s71, s15, s75
	s_mov_b32 m0, s69
	v_readfirstlane_b32 s69, v154
	global_load_lds_dwordx4 v134, s[70:71]
	s_mov_b32 m0, s69
	s_ashr_i32 s69, s68, 31
	s_lshl_b64 s[76:77], s[68:69], 13
	v_lshl_add_u64 v[0:1], s[70:71], 0, v[134:135]
	v_lshl_add_u64 v[2:3], s[70:71], 0, v[136:137]
	global_load_lds_dwordx4 v136, s[70:71]
	s_add_u32 s70, s56, s76
	v_readfirstlane_b32 s69, v152
	s_addc_u32 s71, s57, s77
	s_mov_b32 m0, s69
	v_readfirstlane_b32 s69, v155
	global_load_lds_dwordx4 v134, s[70:71]
	s_mov_b32 m0, s69
	v_lshl_add_u64 v[4:5], s[70:71], 0, v[134:135]
	v_lshl_add_u64 v[6:7], s[70:71], 0, v[136:137]
	global_load_lds_dwordx4 v136, s[70:71]
	s_or_b32 s70, s66, 0x80
	s_ashr_i32 s71, s70, 31
	s_lshl_b64 s[70:71], s[70:71], 13
	s_add_u32 s70, s3, s70
	v_readfirstlane_b32 s69, v156
	s_addc_u32 s71, s15, s71
	s_mov_b32 m0, s69
	v_readfirstlane_b32 s69, v157
	global_load_lds_dwordx4 v134, s[70:71]
	s_mov_b32 m0, s69
	v_lshl_add_u64 v[8:9], s[70:71], 0, v[134:135]
	v_lshl_add_u64 v[10:11], s[70:71], 0, v[136:137]
	global_load_lds_dwordx4 v136, s[70:71]
	s_or_b32 s70, s68, 0x80
	s_ashr_i32 s71, s70, 31
	s_lshl_b64 s[72:73], s[70:71], 13
	s_add_u32 s72, s56, s72
	v_readfirstlane_b32 s69, v158
	s_addc_u32 s73, s57, s73
	s_mov_b32 m0, s69
	v_readfirstlane_b32 s69, v159
	global_load_lds_dwordx4 v134, s[72:73]
	s_mov_b32 m0, s69
	v_readfirstlane_b32 s69, v160
	global_load_lds_dwordx4 v136, s[72:73]
	v_lshl_add_u64 v[0:1], v[0:1], 0, s[38:39]
	s_mov_b32 m0, s69
	v_readfirstlane_b32 s69, v161
	global_load_lds_dwordx4 v[0:1], off
	v_lshl_add_u64 v[0:1], v[2:3], 0, s[38:39]
	s_mov_b32 m0, s69
	v_readfirstlane_b32 s69, v162
	global_load_lds_dwordx4 v[0:1], off
	v_lshl_add_u64 v[0:1], v[4:5], 0, s[38:39]
	s_mov_b32 m0, s69
	v_readfirstlane_b32 s69, v163
	global_load_lds_dwordx4 v[0:1], off
	v_lshl_add_u64 v[0:1], v[6:7], 0, s[38:39]
	s_mov_b32 m0, s69
	v_readfirstlane_b32 s69, v165
	global_load_lds_dwordx4 v[0:1], off
	v_lshl_add_u64 v[0:1], v[8:9], 0, s[38:39]
	s_mov_b32 m0, s69
	v_readfirstlane_b32 s69, v166
	global_load_lds_dwordx4 v[0:1], off
	v_lshl_add_u64 v[0:1], v[10:11], 0, s[38:39]
	s_mov_b32 m0, s69
	s_nop 0
	global_load_lds_dwordx4 v[0:1], off
	v_mov_b32_e32 v0, 0
	v_lshl_add_u64 v[138:139], v[130:131], 0, s[74:75]
	v_lshl_add_u64 v[140:141], v[132:133], 0, s[74:75]
	v_lshl_add_u64 v[142:143], v[130:131], 0, s[76:77]
	v_lshl_add_u64 v[144:145], v[132:133], 0, s[76:77]
	s_mov_b32 s69, -2
	s_mov_b64 s[74:75], s[56:57]
	v_mov_b32_e32 v1, v0
	v_mov_b32_e32 v2, v0
	v_mov_b32_e32 v3, v0
	v_mov_b32_e32 v4, v0
	v_mov_b32_e32 v5, v0
	v_mov_b32_e32 v6, v0
	v_mov_b32_e32 v7, v0
	v_mov_b32_e32 v8, v0
	v_mov_b32_e32 v9, v0
	v_mov_b32_e32 v10, v0
	v_mov_b32_e32 v11, v0
	v_mov_b32_e32 v12, v0
	v_mov_b32_e32 v13, v0
	v_mov_b32_e32 v14, v0
	v_mov_b32_e32 v15, v0
	v_mov_b32_e32 v16, v0
	v_mov_b32_e32 v17, v0
	v_mov_b32_e32 v18, v0
	v_mov_b32_e32 v19, v0
	v_mov_b32_e32 v20, v0
	v_mov_b32_e32 v21, v0
	v_mov_b32_e32 v22, v0
	v_mov_b32_e32 v23, v0
	v_mov_b32_e32 v24, v0
	v_mov_b32_e32 v25, v0
	v_mov_b32_e32 v26, v0
	v_mov_b32_e32 v27, v0
	v_mov_b32_e32 v28, v0
	v_mov_b32_e32 v29, v0
	v_mov_b32_e32 v30, v0
	v_mov_b32_e32 v31, v0
	v_mov_b32_e32 v32, v0
	v_mov_b32_e32 v33, v0
	v_mov_b32_e32 v34, v0
	v_mov_b32_e32 v35, v0
	v_mov_b32_e32 v36, v0
	v_mov_b32_e32 v37, v0
	v_mov_b32_e32 v38, v0
	v_mov_b32_e32 v39, v0
	v_mov_b32_e32 v40, v0
	v_mov_b32_e32 v41, v0
	v_mov_b32_e32 v42, v0
	v_mov_b32_e32 v43, v0
	v_mov_b32_e32 v44, v0
	v_mov_b32_e32 v45, v0
	v_mov_b32_e32 v46, v0
	v_mov_b32_e32 v47, v0
	v_mov_b32_e32 v48, v0
	v_mov_b32_e32 v49, v0
	v_mov_b32_e32 v50, v0
	v_mov_b32_e32 v51, v0
	v_mov_b32_e32 v52, v0
	v_mov_b32_e32 v53, v0
	v_mov_b32_e32 v54, v0
	v_mov_b32_e32 v55, v0
	v_mov_b32_e32 v56, v0
	v_mov_b32_e32 v57, v0
	v_mov_b32_e32 v58, v0
	v_mov_b32_e32 v59, v0
	v_mov_b32_e32 v60, v0
	v_mov_b32_e32 v61, v0
	v_mov_b32_e32 v62, v0
	v_mov_b32_e32 v63, v0
	v_mov_b32_e32 v64, v0
	v_mov_b32_e32 v65, v0
	v_mov_b32_e32 v66, v0
	v_mov_b32_e32 v67, v0
	v_mov_b32_e32 v68, v0
	v_mov_b32_e32 v69, v0
	v_mov_b32_e32 v70, v0
	v_mov_b32_e32 v71, v0
	v_mov_b32_e32 v72, v0
	v_mov_b32_e32 v73, v0
	v_mov_b32_e32 v74, v0
	v_mov_b32_e32 v75, v0
	v_mov_b32_e32 v76, v0
	v_mov_b32_e32 v77, v0
	v_mov_b32_e32 v78, v0
	v_mov_b32_e32 v79, v0
	v_mov_b32_e32 v80, v0
	v_mov_b32_e32 v81, v0
	v_mov_b32_e32 v82, v0
	v_mov_b32_e32 v83, v0
	v_mov_b32_e32 v84, v0
	v_mov_b32_e32 v85, v0
	v_mov_b32_e32 v86, v0
	v_mov_b32_e32 v87, v0
	v_mov_b32_e32 v88, v0
	v_mov_b32_e32 v89, v0
	v_mov_b32_e32 v90, v0
	v_mov_b32_e32 v91, v0
	v_mov_b32_e32 v92, v0
	v_mov_b32_e32 v93, v0
	v_mov_b32_e32 v94, v0
	v_mov_b32_e32 v95, v0
	v_mov_b32_e32 v96, v0
	v_mov_b32_e32 v97, v0
	v_mov_b32_e32 v98, v0
	v_mov_b32_e32 v99, v0
	v_mov_b32_e32 v100, v0
	v_mov_b32_e32 v101, v0
	v_mov_b32_e32 v102, v0
	v_mov_b32_e32 v103, v0
	v_mov_b32_e32 v104, v0
	v_mov_b32_e32 v105, v0
	v_mov_b32_e32 v106, v0
	v_mov_b32_e32 v107, v0
	v_mov_b32_e32 v108, v0
	v_mov_b32_e32 v109, v0
	v_mov_b32_e32 v110, v0
	v_mov_b32_e32 v111, v0
	v_mov_b32_e32 v112, v0
	v_mov_b32_e32 v113, v0
	v_mov_b32_e32 v114, v0
	v_mov_b32_e32 v115, v0
	v_mov_b32_e32 v116, v0
	v_mov_b32_e32 v117, v0
	v_mov_b32_e32 v118, v0
	v_mov_b32_e32 v119, v0
	v_mov_b32_e32 v120, v0
	v_mov_b32_e32 v121, v0
	v_mov_b32_e32 v122, v0
	v_mov_b32_e32 v123, v0
	v_mov_b32_e32 v124, v0
	v_mov_b32_e32 v125, v0
	v_mov_b32_e32 v126, v0
	v_mov_b32_e32 v127, v0
	v_readfirstlane_b32 s32, v152
	s_waitcnt vmcnt(6)
	s_and_saveexec_b64 s[78:79], s[4:5]
	s_cbranch_execz .LBB0_153
	s_barrier
.LBB0_153:
	s_or_b64 exec, exec, s[78:79]
	s_barrier

; #define STAGE(Pp, BASE, br, kt) do { const u16* _g = (BASE) + ((long)(br) * K + (long)(kt) * BK); \
;     __builtin_amdgcn_global_load_lds((const unsigned*)(_g + voff0), (unsigned*)((char*)(Pp) + tb16), 16, 0, 0); \
;     __builtin_amdgcn_global_load_lds((const unsigned*)(_g + voff1), (unsigned*)((char*)(Pp) + tb16 + 8192), 16, 0, 0); } while (0)
; #define WAIT_V(n) asm volatile("s_waitcnt vmcnt(" #n ")" ::: "memory")
; #define BAR __builtin_amdgcn_s_barrier()
; template <int MODE> ...
;     ...
;     { int q = nwg / NXCD, r = nwg % NXCD, xcd = wgid % NXCD, off = wgid / NXCD;
;       wgid = (xcd < r ? xcd * (q + 1) : r * (q + 1) + (xcd - r) * q) + off; }
;     int nig = WGM * nN, gid = wgid / nig, fm = gid * WGM, gsz = min(nM - fm, WGM);
;     int pm = fm + ((wgid % nig) % gsz), pn = (wgid % nig) / gsz, brow = pm * BM, bcol = pn * BM;
;     f32x4 acc[2][2][4][2] = {};
;     bf16x8 At[4][2], B0[2][2], B1[2][2];
;     ...
;     STAGE(SB(0, 0), Bt, bcol, 0); STAGE(SA(0, 0), A, brow, 0); STAGE(SB(0, 1), Bt, bcol + HALF, 0); STAGE(SA(0, 1), A, brow + HALF, 0);
;     STAGE(SB(1, 0), Bt, bcol, 1); STAGE(SA(1, 0), A, brow, 1); STAGE(SB(1, 1), Bt, bcol + HALF, 1);
;     WAIT_V(6);
;     if (wr == 1) BAR;
;     BAR;
.LBB0_483:
	s_ashr_i32 s63, s63, 3
	s_add_i32 s63, s67, s63
	s_ashr_i32 s64, s63, 31
	s_lshr_b32 s64, s64, 25
	s_add_i32 s64, s63, s64
	s_and_b32 s65, s64, 0xff80
	s_sub_i32 s63, s63, s65
	s_bfe_i32 s65, s63, 0x80000
	s_bfe_u32 s65, s65, 0x3000c
	s_add_i32 s65, s63, s65
	s_bfe_i32 s66, s65, 0x80000
	s_and_b32 s65, s65, 0xf8
	s_sub_i32 s63, s63, s65
	s_sext_i32_i8 s63, s63
	s_lshl_b32 s64, s64, 4
	s_sext_i32_i16 s67, s66
	s_and_b32 s64, s64, 0xfffff800
	s_lshl_b32 s63, s63, 8
	s_add_i32 s66, s63, s64
	s_lshl_b32 s63, s67, 5
	s_and_b32 s68, s63, 0xffffff00
	s_ashr_i32 s69, s68, 31
	s_lshl_b64 s[72:73], s[68:69], 13
	s_add_u32 s64, s33, s72
	v_readfirstlane_b32 s63, v147
	s_addc_u32 s65, s34, s73
	s_mov_b32 m0, s63
	v_readfirstlane_b32 s63, v148
	s_ashr_i32 s67, s66, 31
	global_load_lds_dwordx4 v132, s[64:65]
	s_mov_b32 m0, s63
	s_lshl_b64 s[74:75], s[66:67], 13
	v_lshl_add_u64 v[0:1], s[64:65], 0, v[132:133]
	v_lshl_add_u64 v[2:3], s[64:65], 0, v[134:135]
	global_load_lds_dwordx4 v134, s[64:65]
	s_add_u32 s64, s3, s74
	v_readfirstlane_b32 s63, v146
	s_addc_u32 s65, s15, s75
	s_mov_b32 m0, s63
	v_readfirstlane_b32 s63, v149
	global_load_lds_dwordx4 v132, s[64:65]
	s_mov_b32 m0, s63
	v_lshl_add_u64 v[4:5], s[64:65], 0, v[132:133]
	v_lshl_add_u64 v[6:7], s[64:65], 0, v[134:135]
	global_load_lds_dwordx4 v134, s[64:65]
	s_or_b32 s64, s68, 0x80
	s_ashr_i32 s65, s64, 31
	s_lshl_b64 s[64:65], s[64:65], 13
	s_add_u32 s64, s33, s64
	v_readfirstlane_b32 s63, v150
	s_addc_u32 s65, s34, s65
	s_mov_b32 m0, s63
	v_readfirstlane_b32 s63, v151
	global_load_lds_dwordx4 v132, s[64:65]
	s_mov_b32 m0, s63
	v_lshl_add_u64 v[8:9], s[64:65], 0, v[132:133]
	v_lshl_add_u64 v[10:11], s[64:65], 0, v[134:135]
	global_load_lds_dwordx4 v134, s[64:65]
	s_or_b32 s64, s66, 0x80
	s_ashr_i32 s65, s64, 31
	s_lshl_b64 s[70:71], s[64:65], 13
	s_add_u32 s70, s3, s70
	v_readfirstlane_b32 s63, v152
	s_addc_u32 s71, s15, s71
	s_mov_b32 m0, s63
	v_readfirstlane_b32 s63, v153
	global_load_lds_dwordx4 v132, s[70:71]
	s_mov_b32 m0, s63
	v_readfirstlane_b32 s63, v154
	global_load_lds_dwordx4 v134, s[70:71]
	v_lshl_add_u64 v[0:1], v[0:1], 0, s[12:13]
	s_mov_b32 m0, s63
	v_readfirstlane_b32 s63, v155
	global_load_lds_dwordx4 v[0:1], off
	v_lshl_add_u64 v[0:1], v[2:3], 0, s[12:13]
	s_mov_b32 m0, s63
	v_readfirstlane_b32 s63, v156
	global_load_lds_dwordx4 v[0:1], off
	v_lshl_add_u64 v[0:1], v[4:5], 0, s[12:13]
	s_mov_b32 m0, s63
	v_readfirstlane_b32 s63, v157
	global_load_lds_dwordx4 v[0:1], off
	v_lshl_add_u64 v[0:1], v[6:7], 0, s[12:13]
	s_mov_b32 m0, s63
	v_readfirstlane_b32 s63, v158
	global_load_lds_dwordx4 v[0:1], off
	v_lshl_add_u64 v[0:1], v[8:9], 0, s[12:13]
	s_mov_b32 m0, s63
	v_readfirstlane_b32 s63, v159
	global_load_lds_dwordx4 v[0:1], off
	v_lshl_add_u64 v[0:1], v[10:11], 0, s[12:13]
	s_mov_b32 m0, s63
	s_nop 0
	global_load_lds_dwordx4 v[0:1], off
	v_mov_b32_e32 v0, 0
	v_lshl_add_u64 v[136:137], v[130:131], 0, s[72:73]
	v_lshl_add_u64 v[138:139], v[128:129], 0, s[72:73]
	v_lshl_add_u64 v[140:141], v[130:131], 0, s[74:75]
	v_lshl_add_u64 v[142:143], v[128:129], 0, s[74:75]
	s_mov_b32 s63, -2
	s_mov_b64 s[72:73], s[56:57]
	v_mov_b32_e32 v1, v0
	v_mov_b32_e32 v2, v0
	v_mov_b32_e32 v3, v0
	v_mov_b32_e32 v4, v0
	v_mov_b32_e32 v5, v0
	v_mov_b32_e32 v6, v0
	v_mov_b32_e32 v7, v0
	v_mov_b32_e32 v8, v0
	v_mov_b32_e32 v9, v0
	v_mov_b32_e32 v10, v0
	v_mov_b32_e32 v11, v0
	v_mov_b32_e32 v12, v0
	v_mov_b32_e32 v13, v0
	v_mov_b32_e32 v14, v0
	v_mov_b32_e32 v15, v0
	v_mov_b32_e32 v16, v0
	v_mov_b32_e32 v17, v0
	v_mov_b32_e32 v18, v0
	v_mov_b32_e32 v19, v0
	v_mov_b32_e32 v20, v0
	v_mov_b32_e32 v21, v0
	v_mov_b32_e32 v22, v0
	v_mov_b32_e32 v23, v0
	v_mov_b32_e32 v24, v0
	v_mov_b32_e32 v25, v0
	v_mov_b32_e32 v26, v0
	v_mov_b32_e32 v27, v0
	v_mov_b32_e32 v28, v0
	v_mov_b32_e32 v29, v0
	v_mov_b32_e32 v30, v0
	v_mov_b32_e32 v31, v0
	v_mov_b32_e32 v32, v0
	v_mov_b32_e32 v33, v0
	v_mov_b32_e32 v34, v0
	v_mov_b32_e32 v35, v0
	v_mov_b32_e32 v36, v0
	v_mov_b32_e32 v37, v0
	v_mov_b32_e32 v38, v0
	v_mov_b32_e32 v39, v0
	v_mov_b32_e32 v40, v0
	v_mov_b32_e32 v41, v0
	v_mov_b32_e32 v42, v0
	v_mov_b32_e32 v43, v0
	v_mov_b32_e32 v44, v0
	v_mov_b32_e32 v45, v0
	v_mov_b32_e32 v46, v0
	v_mov_b32_e32 v47, v0
	v_mov_b32_e32 v48, v0
	v_mov_b32_e32 v49, v0
	v_mov_b32_e32 v50, v0
	v_mov_b32_e32 v51, v0
	v_mov_b32_e32 v52, v0
	v_mov_b32_e32 v53, v0
	v_mov_b32_e32 v54, v0
	v_mov_b32_e32 v55, v0
	v_mov_b32_e32 v56, v0
	v_mov_b32_e32 v57, v0
	v_mov_b32_e32 v58, v0
	v_mov_b32_e32 v59, v0
	v_mov_b32_e32 v60, v0
	v_mov_b32_e32 v61, v0
	v_mov_b32_e32 v62, v0
	v_mov_b32_e32 v63, v0
	v_mov_b32_e32 v64, v0
	v_mov_b32_e32 v65, v0
	v_mov_b32_e32 v66, v0
	v_mov_b32_e32 v67, v0
	v_mov_b32_e32 v68, v0
	v_mov_b32_e32 v69, v0
	v_mov_b32_e32 v70, v0
	v_mov_b32_e32 v71, v0
	v_mov_b32_e32 v72, v0
	v_mov_b32_e32 v73, v0
	v_mov_b32_e32 v74, v0
	v_mov_b32_e32 v75, v0
	v_mov_b32_e32 v76, v0
	v_mov_b32_e32 v77, v0
	v_mov_b32_e32 v78, v0
	v_mov_b32_e32 v79, v0
	v_mov_b32_e32 v80, v0
	v_mov_b32_e32 v81, v0
	v_mov_b32_e32 v82, v0
	v_mov_b32_e32 v83, v0
	v_mov_b32_e32 v84, v0
	v_mov_b32_e32 v85, v0
	v_mov_b32_e32 v86, v0
	v_mov_b32_e32 v87, v0
	v_mov_b32_e32 v88, v0
	v_mov_b32_e32 v89, v0
	v_mov_b32_e32 v90, v0
	v_mov_b32_e32 v91, v0
	v_mov_b32_e32 v92, v0
	v_mov_b32_e32 v93, v0
	v_mov_b32_e32 v94, v0
	v_mov_b32_e32 v95, v0
	v_mov_b32_e32 v96, v0
	v_mov_b32_e32 v97, v0
	v_mov_b32_e32 v98, v0
	v_mov_b32_e32 v99, v0
	v_mov_b32_e32 v100, v0
	v_mov_b32_e32 v101, v0
	v_mov_b32_e32 v102, v0
	v_mov_b32_e32 v103, v0
	v_mov_b32_e32 v104, v0
	v_mov_b32_e32 v105, v0
	v_mov_b32_e32 v106, v0
	v_mov_b32_e32 v107, v0
	v_mov_b32_e32 v108, v0
	v_mov_b32_e32 v109, v0
	v_mov_b32_e32 v110, v0
	v_mov_b32_e32 v111, v0
	v_mov_b32_e32 v112, v0
	v_mov_b32_e32 v113, v0
	v_mov_b32_e32 v114, v0
	v_mov_b32_e32 v115, v0
	v_mov_b32_e32 v116, v0
	v_mov_b32_e32 v117, v0
	v_mov_b32_e32 v118, v0
	v_mov_b32_e32 v119, v0
	v_mov_b32_e32 v120, v0
	v_mov_b32_e32 v121, v0
	v_mov_b32_e32 v122, v0
	v_mov_b32_e32 v123, v0
	v_mov_b32_e32 v124, v0
	v_mov_b32_e32 v125, v0
	v_mov_b32_e32 v126, v0
	v_mov_b32_e32 v127, v0
	v_readfirstlane_b32 s32, v146
	s_waitcnt vmcnt(6)
	s_and_saveexec_b64 s[76:77], s[4:5]
	s_cbranch_execz .LBB0_485
	s_barrier
.LBB0_485:
	s_or_b64 exec, exec, s[76:77]
	s_barrier

; #define STAGE(Pp, BASE, br, kt) do { const u16* _g = (BASE) + ((long)(br) * K + (long)(kt) * BK); \
;     __builtin_amdgcn_global_load_lds((const unsigned*)(_g + voff0), (unsigned*)((char*)(Pp) + tb16), 16, 0, 0); \
;     __builtin_amdgcn_global_load_lds((const unsigned*)(_g + voff1), (unsigned*)((char*)(Pp) + tb16 + 8192), 16, 0, 0); } while (0)
; #define WAIT_V(n) asm volatile("s_waitcnt vmcnt(" #n ")" ::: "memory")
; #define BAR __builtin_amdgcn_s_barrier()
; template <int MODE> ...
;     ...
;     { int q = nwg / NXCD, r = nwg % NXCD, xcd = wgid % NXCD, off = wgid / NXCD;
;       wgid = (xcd < r ? xcd * (q + 1) : r * (q + 1) + (xcd - r) * q) + off; }
;     int nig = WGM * nN, gid = wgid / nig, fm = gid * WGM, gsz = min(nM - fm, WGM);
;     int pm = fm + ((wgid % nig) % gsz), pn = (wgid % nig) / gsz, brow = pm * BM, bcol = pn * BM;
;     f32x4 acc[2][2][4][2] = {};
;     bf16x8 At[4][2], B0[2][2], B1[2][2];
;     ...
;     STAGE(SB(0, 0), Bt, bcol, 0); STAGE(SA(0, 0), A, brow, 0); STAGE(SB(0, 1), Bt, bcol + HALF, 0); STAGE(SA(0, 1), A, brow + HALF, 0);
;     STAGE(SB(1, 0), Bt, bcol, 1); STAGE(SA(1, 0), A, brow, 1); STAGE(SB(1, 1), Bt, bcol + HALF, 1);
;     WAIT_V(6);
;     if (wr == 1) BAR;
;     BAR;
.LBB0_588:
	s_ashr_i32 s8, s85, 31
	s_lshr_b32 s8, s8, 29
	s_add_i32 s8, s85, s8
	s_ashr_i32 s9, s8, 3
	s_and_b32 s8, s8, -8
	s_sub_i32 s8, s85, s8
	s_cmp_lt_i32 s8, 0
	s_cselect_b32 s10, s72, 0x158
	s_mul_i32 s8, s10, s8
	s_add_i32 s8, s8, s9
	s_mul_hi_i32 s9, s8, 0x2fa0be83
	s_lshr_b32 s10, s9, 31
	s_ashr_i32 s9, s9, 7
	s_add_i32 s9, s9, s10
	s_lshl_b32 s86, s9, 3
	s_mulk_i32 s9, 0x2b0
	s_sub_i32 s8, s8, s9
	s_sext_i32_i16 s9, s8
	s_bfe_u32 s9, s9, 0x3001c
	s_add_i32 s9, s8, s9
	s_sext_i32_i16 s10, s9
	s_and_b32 s9, s9, 0xfff8
	s_sub_i32 s8, s8, s9
	s_sext_i32_i16 s8, s8
	s_ashr_i32 s34, s10, 3
	s_add_i32 s86, s86, s8
	s_lshl_b32 s8, s34, 8
	s_ashr_i32 s9, s8, 31
	s_lshl_b32 s64, s86, 8
	s_lshl_b64 s[10:11], s[8:9], 13
	s_add_u32 s66, s16, s10
	v_readfirstlane_b32 s9, v151
	s_addc_u32 s67, s17, s11
	s_mov_b32 m0, s9
	v_readfirstlane_b32 s9, v152
	global_load_lds_dwordx4 v134, s[66:67]
	s_mov_b32 m0, s9
	s_ashr_i32 s65, s64, 31
	v_lshl_add_u64 v[0:1], s[66:67], 0, v[134:135]
	v_lshl_add_u64 v[2:3], s[66:67], 0, v[136:137]
	global_load_lds_dwordx4 v136, s[66:67]
	s_lshl_b64 s[66:67], s[64:65], 13
	s_add_u32 s68, s56, s66
	v_readfirstlane_b32 s9, v150
	s_addc_u32 s69, s57, s67
	s_mov_b32 m0, s9
	v_readfirstlane_b32 s9, v153
	s_bitset1_b32 s8, 7
	global_load_lds_dwordx4 v134, s[68:69]
	s_mov_b32 m0, s9
	s_ashr_i32 s9, s8, 31
	s_lshl_b64 s[8:9], s[8:9], 13
	s_add_u32 s8, s16, s8
	v_readfirstlane_b32 s35, v154
	global_load_lds_dwordx4 v136, s[68:69]
	s_addc_u32 s9, s17, s9
	s_mov_b32 m0, s35
	v_readfirstlane_b32 s35, v155
	global_load_lds_dwordx4 v134, s[8:9]
	s_mov_b32 m0, s35
	v_lshl_add_u64 v[8:9], s[8:9], 0, v[134:135]
	v_lshl_add_u64 v[10:11], s[8:9], 0, v[136:137]
	global_load_lds_dwordx4 v136, s[8:9]
	s_or_b32 s8, s64, 0x80
	s_ashr_i32 s9, s8, 31
	s_lshl_b64 s[8:9], s[8:9], 13
	s_add_u32 s8, s56, s8
	v_readfirstlane_b32 s35, v156
	s_addc_u32 s9, s57, s9
	s_mov_b32 m0, s35
	v_readfirstlane_b32 s35, v157
	global_load_lds_dwordx4 v134, s[8:9]
	s_mov_b32 m0, s35
	v_readfirstlane_b32 s35, v158
	global_load_lds_dwordx4 v136, s[8:9]
	v_lshl_add_u64 v[0:1], v[0:1], 0, s[36:37]
	s_mov_b32 m0, s35
	v_readfirstlane_b32 s35, v159
	v_lshl_add_u64 v[4:5], s[68:69], 0, v[134:135]
	global_load_lds_dwordx4 v[0:1], off
	v_lshl_add_u64 v[0:1], v[2:3], 0, s[36:37]
	s_mov_b32 m0, s35
	v_readfirstlane_b32 s35, v160
	v_lshl_add_u64 v[6:7], s[68:69], 0, v[136:137]
	global_load_lds_dwordx4 v[0:1], off
	v_lshl_add_u64 v[0:1], v[4:5], 0, s[36:37]
	s_mov_b32 m0, s35
	v_readfirstlane_b32 s35, v161
	global_load_lds_dwordx4 v[0:1], off
	v_lshl_add_u64 v[0:1], v[6:7], 0, s[36:37]
	s_mov_b32 m0, s35
	v_readfirstlane_b32 s35, v162
	global_load_lds_dwordx4 v[0:1], off
	v_lshl_add_u64 v[0:1], v[8:9], 0, s[36:37]
	s_mov_b32 m0, s35
	v_readfirstlane_b32 s35, v163
	global_load_lds_dwordx4 v[0:1], off
	v_lshl_add_u64 v[0:1], v[10:11], 0, s[36:37]
	s_mov_b32 m0, s35
	s_nop 0
	global_load_lds_dwordx4 v[0:1], off
	v_mov_b32_e32 v0, 0
	v_lshl_add_u64 v[138:139], v[146:147], 0, s[10:11]
	v_lshl_add_u64 v[140:141], v[252:253], 0, s[10:11]
	v_lshl_add_u64 v[142:143], v[146:147], 0, s[66:67]
	v_lshl_add_u64 v[144:145], v[252:253], 0, s[66:67]
	s_mov_b32 s35, -2
	s_mov_b64 s[10:11], s[56:57]
	v_mov_b32_e32 v1, v0
	v_mov_b32_e32 v2, v0
	v_mov_b32_e32 v3, v0
	v_mov_b32_e32 v4, v0
	v_mov_b32_e32 v5, v0
	v_mov_b32_e32 v6, v0
	v_mov_b32_e32 v7, v0
	v_mov_b32_e32 v8, v0
	v_mov_b32_e32 v9, v0
	v_mov_b32_e32 v10, v0
	v_mov_b32_e32 v11, v0
	v_mov_b32_e32 v12, v0
	v_mov_b32_e32 v13, v0
	v_mov_b32_e32 v14, v0
	v_mov_b32_e32 v15, v0
	v_mov_b32_e32 v16, v0
	v_mov_b32_e32 v17, v0
	v_mov_b32_e32 v18, v0
	v_mov_b32_e32 v19, v0
	v_mov_b32_e32 v20, v0
	v_mov_b32_e32 v21, v0
	v_mov_b32_e32 v22, v0
	v_mov_b32_e32 v23, v0
	v_mov_b32_e32 v24, v0
	v_mov_b32_e32 v25, v0
	v_mov_b32_e32 v26, v0
	v_mov_b32_e32 v27, v0
	v_mov_b32_e32 v28, v0
	v_mov_b32_e32 v29, v0
	v_mov_b32_e32 v30, v0
	v_mov_b32_e32 v31, v0
	v_mov_b32_e32 v32, v0
	v_mov_b32_e32 v33, v0
	v_mov_b32_e32 v34, v0
	v_mov_b32_e32 v35, v0
	v_mov_b32_e32 v36, v0
	v_mov_b32_e32 v37, v0
	v_mov_b32_e32 v38, v0
	v_mov_b32_e32 v39, v0
	v_mov_b32_e32 v40, v0
	v_mov_b32_e32 v41, v0
	v_mov_b32_e32 v42, v0
	v_mov_b32_e32 v43, v0
	v_mov_b32_e32 v44, v0
	v_mov_b32_e32 v45, v0
	v_mov_b32_e32 v46, v0
	v_mov_b32_e32 v47, v0
	v_mov_b32_e32 v48, v0
	v_mov_b32_e32 v49, v0
	v_mov_b32_e32 v50, v0
	v_mov_b32_e32 v51, v0
	v_mov_b32_e32 v56, v0
	v_mov_b32_e32 v57, v0
	v_mov_b32_e32 v58, v0
	v_mov_b32_e32 v59, v0
	v_mov_b32_e32 v72, v0
	v_mov_b32_e32 v73, v0
	v_mov_b32_e32 v74, v0
	v_mov_b32_e32 v75, v0
	v_mov_b32_e32 v88, v0
	v_mov_b32_e32 v89, v0
	v_mov_b32_e32 v90, v0
	v_mov_b32_e32 v91, v0
	v_mov_b32_e32 v96, v0
	v_mov_b32_e32 v97, v0
	v_mov_b32_e32 v98, v0
	v_mov_b32_e32 v99, v0
	v_mov_b32_e32 v100, v0
	v_mov_b32_e32 v101, v0
	v_mov_b32_e32 v102, v0
	v_mov_b32_e32 v103, v0
	v_mov_b32_e32 v104, v0
	v_mov_b32_e32 v105, v0
	v_mov_b32_e32 v106, v0
	v_mov_b32_e32 v107, v0
	v_mov_b32_e32 v108, v0
	v_mov_b32_e32 v109, v0
	v_mov_b32_e32 v110, v0
	v_mov_b32_e32 v111, v0
	v_mov_b32_e32 v112, v0
	v_mov_b32_e32 v113, v0
	v_mov_b32_e32 v114, v0
	v_mov_b32_e32 v115, v0
	v_mov_b32_e32 v116, v0
	v_mov_b32_e32 v117, v0
	v_mov_b32_e32 v118, v0
	v_mov_b32_e32 v119, v0
	v_mov_b32_e32 v120, v0
	v_mov_b32_e32 v121, v0
	v_mov_b32_e32 v122, v0
	v_mov_b32_e32 v123, v0
	v_mov_b32_e32 v124, v0
	v_mov_b32_e32 v125, v0
	v_mov_b32_e32 v126, v0
	v_mov_b32_e32 v127, v0
	v_mov_b32_e32 v52, v0
	v_mov_b32_e32 v53, v0
	v_mov_b32_e32 v54, v0
	v_mov_b32_e32 v55, v0
	v_mov_b32_e32 v60, v0
	v_mov_b32_e32 v61, v0
	v_mov_b32_e32 v62, v0
	v_mov_b32_e32 v63, v0
	v_mov_b32_e32 v64, v0
	v_mov_b32_e32 v65, v0
	v_mov_b32_e32 v66, v0
	v_mov_b32_e32 v67, v0
	v_mov_b32_e32 v68, v0
	v_mov_b32_e32 v69, v0
	v_mov_b32_e32 v70, v0
	v_mov_b32_e32 v71, v0
	v_mov_b32_e32 v76, v0
	v_mov_b32_e32 v77, v0
	v_mov_b32_e32 v78, v0
	v_mov_b32_e32 v79, v0
	v_mov_b32_e32 v80, v0
	v_mov_b32_e32 v81, v0
	v_mov_b32_e32 v82, v0
	v_mov_b32_e32 v83, v0
	v_mov_b32_e32 v84, v0
	v_mov_b32_e32 v85, v0
	v_mov_b32_e32 v86, v0
	v_mov_b32_e32 v87, v0
	v_mov_b32_e32 v92, v0
	v_mov_b32_e32 v93, v0
	v_mov_b32_e32 v94, v0
	v_mov_b32_e32 v95, v0
	v_readfirstlane_b32 s32, v150
	s_waitcnt vmcnt(6)
	s_and_saveexec_b64 s[68:69], s[4:5]
	s_cbranch_execz .LBB0_590
	s_barrier
.LBB0_590:
	s_or_b64 exec, exec, s[68:69]
	s_barrier

; #define STAGE(Pp, BASE, br, kt) do { const u16* _g = (BASE) + ((long)(br) * K + (long)(kt) * BK); \
;     __builtin_amdgcn_global_load_lds((const unsigned*)(_g + voff0), (unsigned*)((char*)(Pp) + tb16), 16, 0, 0); \
;     __builtin_amdgcn_global_load_lds((const unsigned*)(_g + voff1), (unsigned*)((char*)(Pp) + tb16 + 8192), 16, 0, 0); } while (0)
; #define WAIT_V(n) asm volatile("s_waitcnt vmcnt(" #n ")" ::: "memory")
; #define BAR __builtin_amdgcn_s_barrier()
; template <int MODE> ...
;     ...
;     { int q = nwg / NXCD, r = nwg % NXCD, xcd = wgid % NXCD, off = wgid / NXCD;
;       wgid = (xcd < r ? xcd * (q + 1) : r * (q + 1) + (xcd - r) * q) + off; }
;     int nig = WGM * nN, gid = wgid / nig, fm = gid * WGM, gsz = min(nM - fm, WGM);
;     int pm = fm + ((wgid % nig) % gsz), pn = (wgid % nig) / gsz, brow = pm * BM, bcol = pn * BM;
;     f32x4 acc[2][2][4][2] = {};
;     bf16x8 At[4][2], B0[2][2], B1[2][2];
;     ...
;     STAGE(SB(0, 0), Bt, bcol, 0); STAGE(SA(0, 0), A, brow, 0); STAGE(SB(0, 1), Bt, bcol + HALF, 0); STAGE(SA(0, 1), A, brow + HALF, 0);
;     STAGE(SB(1, 0), Bt, bcol, 1); STAGE(SA(1, 0), A, brow, 1); STAGE(SB(1, 1), Bt, bcol + HALF, 1);
;     WAIT_V(6);
;     if (wr == 1) BAR;
;     BAR;
.LBB0_845:
	s_ashr_i32 s45, s45, 3
	s_add_i32 s45, s49, s45
	s_ashr_i32 s46, s45, 31
	s_lshr_b32 s46, s46, 25
	s_add_i32 s46, s45, s46
	s_and_b32 s47, s46, 0xff80
	s_sub_i32 s45, s45, s47
	s_bfe_i32 s47, s45, 0x80000
	s_bfe_u32 s47, s47, 0x3000c
	s_add_i32 s47, s45, s47
	s_bfe_i32 s48, s47, 0x80000
	s_and_b32 s47, s47, 0xf8
	s_sub_i32 s45, s45, s47
	s_sext_i32_i16 s48, s48
	s_sext_i32_i8 s45, s45
	s_lshl_b32 s46, s46, 4
	s_ashr_i32 s49, s48, 3
	s_and_b32 s46, s46, 0xfffff800
	s_lshl_b32 s45, s45, 8
	s_add_i32 s48, s45, s46
	s_lshl_b32 s50, s49, 8
	s_mul_i32 s62, s49, 0x560000
	s_mul_hi_i32 s63, s50, 0x5600
	s_add_u32 s46, s33, s62
	v_readfirstlane_b32 s45, v153
	s_addc_u32 s47, s34, s63
	s_mov_b32 m0, s45
	v_readfirstlane_b32 s45, v154
	global_load_lds_dwordx4 v134, s[46:47]
	s_mov_b32 m0, s45
	s_mul_i32 s64, s48, 0x5600
	v_lshl_add_u64 v[0:1], s[46:47], 0, v[134:135]
	v_lshl_add_u64 v[2:3], s[46:47], 0, v[136:137]
	global_load_lds_dwordx4 v136, s[46:47]
	s_mul_hi_i32 s65, s48, 0x5600
	s_add_u32 s46, s3, s64
	v_readfirstlane_b32 s45, v152
	s_addc_u32 s47, s15, s65
	s_mov_b32 m0, s45
	v_readfirstlane_b32 s45, v155
	global_load_lds_dwordx4 v134, s[46:47]
	s_mov_b32 m0, s45
	v_lshl_add_u64 v[4:5], s[46:47], 0, v[134:135]
	v_lshl_add_u64 v[6:7], s[46:47], 0, v[136:137]
	global_load_lds_dwordx4 v136, s[46:47]
	s_mul_i32 s46, s49, 0x2b0000
	s_ashr_i32 s47, s46, 31
	s_lshl_b64 s[66:67], s[46:47], 1
	s_add_u32 s45, s33, s66
	s_addc_u32 s49, s34, s67
	s_add_u32 s46, s45, 0x2b0000
	v_readfirstlane_b32 s51, v156
	s_addc_u32 s47, s49, 0
	s_mov_b32 m0, s51
	v_readfirstlane_b32 s51, v157
	global_load_lds_dwordx4 v134, s[46:47]
	s_mov_b32 m0, s51
	v_lshl_add_u64 v[0:1], v[0:1], 0, s[16:17]
	global_load_lds_dwordx4 v136, s[46:47]
	s_or_b32 s46, s48, 0x80
	s_mul_i32 s51, s46, 0x5600
	s_mul_hi_i32 s47, s46, 0x5600
	s_add_u32 s60, s3, s51
	s_addc_u32 s61, s15, s47
	v_readfirstlane_b32 s47, v158
	s_mov_b32 m0, s47
	v_readfirstlane_b32 s47, v159
	global_load_lds_dwordx4 v134, s[60:61]
	s_mov_b32 m0, s47
	v_readfirstlane_b32 s47, v160
	global_load_lds_dwordx4 v136, s[60:61]
	s_mov_b32 m0, s47
	v_readfirstlane_b32 s47, v161
	global_load_lds_dwordx4 v[0:1], off
	v_lshl_add_u64 v[0:1], v[2:3], 0, s[16:17]
	s_mov_b32 m0, s47
	v_readfirstlane_b32 s47, v162
	global_load_lds_dwordx4 v[0:1], off
	v_lshl_add_u64 v[0:1], v[4:5], 0, s[16:17]
	s_mov_b32 m0, s47
	v_readfirstlane_b32 s47, v163
	global_load_lds_dwordx4 v[0:1], off
	v_lshl_add_u64 v[0:1], v[6:7], 0, s[16:17]
	s_mov_b32 m0, s47
	s_add_u32 s68, s45, 0x2b0080
	v_readfirstlane_b32 s45, v165
	global_load_lds_dwordx4 v[0:1], off
	s_addc_u32 s69, s49, 0
	s_mov_b32 m0, s45
	v_readfirstlane_b32 s45, v166
	global_load_lds_dwordx4 v134, s[68:69]
	s_mov_b32 m0, s45
	s_nop 0
	global_load_lds_dwordx4 v136, s[68:69]
	v_mov_b32_e32 v0, 0
	s_ashr_i32 s51, s50, 31
	s_ashr_i32 s49, s48, 31
	s_ashr_i32 s47, s46, 31
	v_lshl_add_u64 v[138:139], v[130:131], 0, s[62:63]
	v_lshl_add_u64 v[140:141], v[132:133], 0, s[62:63]
	v_lshl_add_u64 v[142:143], v[130:131], 0, s[66:67]
	v_lshl_add_u64 v[144:145], v[132:133], 0, s[66:67]
	v_lshl_add_u64 v[146:147], v[130:131], 0, s[64:65]
	v_lshl_add_u64 v[148:149], v[132:133], 0, s[64:65]
	s_mov_b32 s45, -2
	s_mov_b64 s[62:63], s[56:57]
	v_mov_b32_e32 v1, v0
	v_mov_b32_e32 v2, v0
	v_mov_b32_e32 v3, v0
	v_mov_b32_e32 v4, v0
	v_mov_b32_e32 v5, v0
	v_mov_b32_e32 v6, v0
	v_mov_b32_e32 v7, v0
	v_mov_b32_e32 v8, v0
	v_mov_b32_e32 v9, v0
	v_mov_b32_e32 v10, v0
	v_mov_b32_e32 v11, v0
	v_mov_b32_e32 v12, v0
	v_mov_b32_e32 v13, v0
	v_mov_b32_e32 v14, v0
	v_mov_b32_e32 v15, v0
	v_mov_b32_e32 v16, v0
	v_mov_b32_e32 v17, v0
	v_mov_b32_e32 v18, v0
	v_mov_b32_e32 v19, v0
	v_mov_b32_e32 v20, v0
	v_mov_b32_e32 v21, v0
	v_mov_b32_e32 v22, v0
	v_mov_b32_e32 v23, v0
	v_mov_b32_e32 v24, v0
	v_mov_b32_e32 v25, v0
	v_mov_b32_e32 v26, v0
	v_mov_b32_e32 v27, v0
	v_mov_b32_e32 v28, v0
	v_mov_b32_e32 v29, v0
	v_mov_b32_e32 v30, v0
	v_mov_b32_e32 v31, v0
	v_mov_b32_e32 v32, v0
	v_mov_b32_e32 v33, v0
	v_mov_b32_e32 v34, v0
	v_mov_b32_e32 v35, v0
	v_mov_b32_e32 v36, v0
	v_mov_b32_e32 v37, v0
	v_mov_b32_e32 v38, v0
	v_mov_b32_e32 v39, v0
	v_mov_b32_e32 v40, v0
	v_mov_b32_e32 v41, v0
	v_mov_b32_e32 v42, v0
	v_mov_b32_e32 v43, v0
	v_mov_b32_e32 v44, v0
	v_mov_b32_e32 v45, v0
	v_mov_b32_e32 v46, v0
	v_mov_b32_e32 v47, v0
	v_mov_b32_e32 v48, v0
	v_mov_b32_e32 v49, v0
	v_mov_b32_e32 v50, v0
	v_mov_b32_e32 v51, v0
	v_mov_b32_e32 v52, v0
	v_mov_b32_e32 v53, v0
	v_mov_b32_e32 v54, v0
	v_mov_b32_e32 v55, v0
	v_mov_b32_e32 v56, v0
	v_mov_b32_e32 v57, v0
	v_mov_b32_e32 v58, v0
	v_mov_b32_e32 v59, v0
	v_mov_b32_e32 v60, v0
	v_mov_b32_e32 v61, v0
	v_mov_b32_e32 v62, v0
	v_mov_b32_e32 v63, v0
	v_mov_b32_e32 v64, v0
	v_mov_b32_e32 v65, v0
	v_mov_b32_e32 v66, v0
	v_mov_b32_e32 v67, v0
	v_mov_b32_e32 v68, v0
	v_mov_b32_e32 v69, v0
	v_mov_b32_e32 v70, v0
	v_mov_b32_e32 v71, v0
	v_mov_b32_e32 v72, v0
	v_mov_b32_e32 v73, v0
	v_mov_b32_e32 v74, v0
	v_mov_b32_e32 v75, v0
	v_mov_b32_e32 v76, v0
	v_mov_b32_e32 v77, v0
	v_mov_b32_e32 v78, v0
	v_mov_b32_e32 v79, v0
	v_mov_b32_e32 v80, v0
	v_mov_b32_e32 v81, v0
	v_mov_b32_e32 v82, v0
	v_mov_b32_e32 v83, v0
	v_mov_b32_e32 v84, v0
	v_mov_b32_e32 v85, v0
	v_mov_b32_e32 v86, v0
	v_mov_b32_e32 v87, v0
	v_mov_b32_e32 v88, v0
	v_mov_b32_e32 v89, v0
	v_mov_b32_e32 v90, v0
	v_mov_b32_e32 v91, v0
	v_mov_b32_e32 v92, v0
	v_mov_b32_e32 v93, v0
	v_mov_b32_e32 v94, v0
	v_mov_b32_e32 v95, v0
	v_mov_b32_e32 v96, v0
	v_mov_b32_e32 v97, v0
	v_mov_b32_e32 v98, v0
	v_mov_b32_e32 v99, v0
	v_mov_b32_e32 v100, v0
	v_mov_b32_e32 v101, v0
	v_mov_b32_e32 v102, v0
	v_mov_b32_e32 v103, v0
	v_mov_b32_e32 v104, v0
	v_mov_b32_e32 v105, v0
	v_mov_b32_e32 v106, v0
	v_mov_b32_e32 v107, v0
	v_mov_b32_e32 v108, v0
	v_mov_b32_e32 v109, v0
	v_mov_b32_e32 v110, v0
	v_mov_b32_e32 v111, v0
	v_mov_b32_e32 v112, v0
	v_mov_b32_e32 v113, v0
	v_mov_b32_e32 v114, v0
	v_mov_b32_e32 v115, v0
	v_mov_b32_e32 v116, v0
	v_mov_b32_e32 v117, v0
	v_mov_b32_e32 v118, v0
	v_mov_b32_e32 v119, v0
	v_mov_b32_e32 v120, v0
	v_mov_b32_e32 v121, v0
	v_mov_b32_e32 v122, v0
	v_mov_b32_e32 v123, v0
	v_mov_b32_e32 v124, v0
	v_mov_b32_e32 v125, v0
	v_mov_b32_e32 v126, v0
	v_mov_b32_e32 v127, v0
	v_readfirstlane_b32 s32, v152
	s_waitcnt vmcnt(6)
	s_and_saveexec_b64 s[68:69], s[4:5]
	s_cbranch_execz .LBB0_847
	s_barrier
